# phase 0 rope tables computed by the last four (otherwise idle) workgroups, one entry per thread per table, instead of six serial entries per thread on one half-block
# speedup vs baseline: 1.0065x; 1.0009x over previous
.LBB0_5:
	s_or_b64 exec, exec, s[4:5]
	s_load_dwordx16 s[52:67], s[0:1], 0x0
	s_load_dwordx16 s[4:19], s[0:1], 0x40
	s_waitcnt lgkmcnt(0)
	v_writelane_b32 v252, s4, 0
	s_nop 1
	v_writelane_b32 v252, s5, 1
	v_writelane_b32 v252, s6, 2
	v_writelane_b32 v252, s7, 3
	v_writelane_b32 v252, s8, 4
	v_writelane_b32 v252, s9, 5
	v_writelane_b32 v252, s10, 6
	v_writelane_b32 v252, s11, 7
	v_writelane_b32 v252, s12, 8
	v_writelane_b32 v252, s13, 9
	v_writelane_b32 v252, s14, 10
	v_writelane_b32 v252, s15, 11
	v_writelane_b32 v252, s16, 12
	v_writelane_b32 v252, s17, 13
	v_writelane_b32 v252, s18, 14
	v_writelane_b32 v252, s19, 15
	s_load_dwordx16 s[4:19], s[0:1], 0x80
	s_add_i32 s0, s22, -4
	s_cmp_lt_u32 s2, s0
	s_waitcnt lgkmcnt(0)
	v_writelane_b32 v252, s4, 16
	s_nop 1
	v_writelane_b32 v252, s5, 17
	v_writelane_b32 v252, s6, 18
	v_writelane_b32 v252, s7, 19
	v_writelane_b32 v252, s8, 20
	v_writelane_b32 v252, s9, 21
	v_writelane_b32 v252, s10, 22
	v_writelane_b32 v252, s11, 23
	v_writelane_b32 v252, s12, 24
	v_writelane_b32 v252, s13, 25
	v_writelane_b32 v252, s14, 26
	v_writelane_b32 v252, s15, 27
	v_writelane_b32 v252, s16, 28
	v_writelane_b32 v252, s17, 29
	v_writelane_b32 v252, s18, 30
	v_writelane_b32 v252, s19, 31
	s_cbranch_scc1 .LBB0_21
	s_movk_i32 s0, 0xff
	v_cmp_lt_u32_e32 vcc, s0, v128
	s_and_saveexec_b64 s[0:1], vcc
	s_xor_b64 s[0:1], exec, s[0:1]
	s_cbranch_execz .LBB0_10
	v_mov_b32_e32 v2, 4
	s_movk_i32 s4, 0xff00
	v_lshlrev_b32_sdwa v2, v2, v128 dst_sel:DWORD dst_unused:UNUSED_PAD src0_sel:DWORD src1_sel:BYTE_0
	v_mov_b32_e32 v3, 0
	v_or_b32_sdwa v1, v128, s4 dst_sel:DWORD dst_unused:UNUSED_PAD src0_sel:BYTE_0 src1_sel:DWORD
	v_lshl_add_u64 v[4:5], s[86:87], 0, v[2:3]
	s_mov_b64 s[4:5], 0x196f000
	v_lshl_add_u64 v[6:7], v[4:5], 0, s[4:5]
	s_mov_b64 s[4:5], 0
	v_mov_b32_e32 v2, v3
	v_mov_b32_e32 v4, v3
	v_mov_b32_e32 v5, v3
	s_mov_b64 s[6:7], 0x1000

.LBB0_10:
	s_andn2_saveexec_b64 s[4:5], s[0:1]
	s_cbranch_execz .LBB0_20
	v_and_b32_e32 v1, 15, v128
	v_cvt_f32_ubyte0_e32 v1, v1
	v_mul_f32_e32 v1, 0xbd800000, v1
	v_mul_f32_e32 v2, 0x41549a78, v1
	s_mov_b32 s0, 0xc2fc0000
	v_mov_b32_e32 v3, 0x42800000
	v_cmp_gt_f32_e32 vcc, s0, v2
	s_add_u32 s6, s86, 0x196c000
	s_mov_b32 s10, 0x54442d18
	v_cndmask_b32_e32 v2, 0, v3, vcc
	v_fmac_f32_e32 v2, 0x41549a78, v1
	v_exp_f32_e32 v1, v2
	v_not_b32_e32 v2, 63
	v_cndmask_b32_e32 v2, 0, v2, vcc
	s_addc_u32 s7, s87, 0
	v_ldexp_f32 v1, v1, v2
	s_mov_b64 s[8:9], 0
	s_mov_b32 s11, 0x401921fb
	v_mov_b32_e32 v3, 0
	s_movk_i32 s12, 0x2ff
	s_sub_i32 s98, s2, s22
	s_add_i32 s98, s98, 4
	s_lshl_b32 s98, s98, 8
	v_add_u32_e32 v2, s98, v128

.LBB0_13:
	s_add_i32 s0, s14, -1
	s_mul_i32 s0, s0, s14
	v_cvt_f64_i32_e32 v[14:15], s0
	s_add_i32 s15, s0, s13
	v_div_scale_f64 v[16:17], s[0:1], v[14:15], v[14:15], v[6:7]
	v_cvt_f64_u32_e32 v[20:21], s15
	v_rcp_f64_e32 v[22:23], v[16:17]
	v_div_scale_f64 v[24:25], s[0:1], v[20:21], v[20:21], v[6:7]
	v_rcp_f64_e32 v[28:29], v[24:25]
	v_fma_f64 v[30:31], -v[16:17], v[22:23], 1.0
	v_fmac_f64_e32 v[22:23], v[22:23], v[30:31]
	v_fma_f64 v[32:33], -v[16:17], v[22:23], 1.0
	v_fma_f64 v[30:31], -v[24:25], v[28:29], 1.0
	v_fmac_f64_e32 v[28:29], v[28:29], v[30:31]
	v_div_scale_f64 v[18:19], vcc, v[6:7], v[14:15], v[6:7]
	v_fmac_f64_e32 v[22:23], v[22:23], v[32:33]
	v_fma_f64 v[30:31], -v[24:25], v[28:29], 1.0
	v_div_scale_f64 v[26:27], s[0:1], v[6:7], v[20:21], v[6:7]
	v_mul_f64 v[32:33], v[18:19], v[22:23]
	v_fmac_f64_e32 v[28:29], v[28:29], v[30:31]
	v_fma_f64 v[16:17], -v[16:17], v[32:33], v[18:19]
	v_mul_f64 v[18:19], v[26:27], v[28:29]
	v_div_fmas_f64 v[16:17], v[16:17], v[22:23], v[32:33]
	v_fma_f64 v[22:23], -v[24:25], v[18:19], v[26:27]
	s_mov_b64 vcc, s[0:1]
	v_div_fixup_f64 v[14:15], v[16:17], v[14:15], v[6:7]
	v_div_fmas_f64 v[16:17], v[22:23], v[28:29], v[18:19]
	v_div_fixup_f64 v[16:17], v[16:17], v[20:21], v[6:7]
	s_add_i32 s14, s14, 2
	s_add_i32 s13, s13, 4
	v_mul_f64 v[18:19], v[4:5], v[14:15]
	v_fmac_f64_e32 v[8:9], v[4:5], v[14:15]
	v_mul_f64 v[14:15], v[10:11], v[16:17]
	s_cmp_lg_u32 s14, 30
	v_fmac_f64_e32 v[12:13], v[10:11], v[16:17]
	v_mov_b64_e32 v[4:5], v[18:19]
	v_mov_b64_e32 v[10:11], v[14:15]
	s_cbranch_scc1 .LBB0_13
	v_cvt_f32_f64_e32 v7, v[8:9]
	v_lshl_add_u64 v[4:5], v[2:3], 2, s[6:7]
	global_store_dword v[4:5], v7, off
	v_add_co_u32_e32 v4, vcc, 0x1000, v4
	v_cvt_f32_f64_e32 v6, v[12:13]
	s_nop 0
	v_addc_co_u32_e32 v5, vcc, 0, v5, vcc
	global_store_dword v[4:5], v6, off
	v_add_u32_e32 v4, 0x100, v2
	s_mov_b64 vcc, exec
	s_or_b64 s[8:9], vcc, s[8:9]
	v_mov_b32_e32 v2, v4
	s_andn2_b64 exec, exec, s[8:9]
	s_cbranch_execnz .LBB0_12
	s_or_b64 exec, exec, s[8:9]
	v_and_b32_e32 v1, 7, v128
	v_cvt_f32_ubyte0_e32 v1, v1
	v_mul_f32_e32 v1, 0xbe000000, v1
	v_mul_f32_e32 v2, 0x41549a78, v1
	s_mov_b32 s0, 0xc2fc0000
	v_mov_b32_e32 v3, 0x42800000
	v_cmp_gt_f32_e32 vcc, s0, v2
	s_add_u32 s6, s86, 0x196e000
	s_mov_b32 s10, 0x54442d18
	v_cndmask_b32_e32 v2, 0, v3, vcc
	v_fmac_f32_e32 v2, 0x41549a78, v1
	v_exp_f32_e32 v1, v2
	v_not_b32_e32 v2, 63
	v_cndmask_b32_e32 v2, 0, v2, vcc
	s_addc_u32 s7, s87, 0
	v_ldexp_f32 v1, v1, v2
	s_mov_b64 s[8:9], 0
	s_mov_b32 s11, 0x401921fb
	v_mov_b32_e32 v3, 0
	s_movk_i32 s12, 0xff
	s_sub_i32 s98, s2, s22
	s_and_b32 s98, s98, 1
	s_lshl_b32 s98, s98, 8
	v_add_u32_e32 v2, s98, v128

.LBB0_17:
	s_add_i32 s0, s14, -1
	s_mul_i32 s0, s0, s14
	v_cvt_f64_i32_e32 v[14:15], s0
	s_add_i32 s15, s0, s13
	v_div_scale_f64 v[16:17], s[0:1], v[14:15], v[14:15], v[6:7]
	v_cvt_f64_u32_e32 v[20:21], s15
	v_rcp_f64_e32 v[22:23], v[16:17]
	v_div_scale_f64 v[24:25], s[0:1], v[20:21], v[20:21], v[6:7]
	v_rcp_f64_e32 v[28:29], v[24:25]
	v_fma_f64 v[30:31], -v[16:17], v[22:23], 1.0
	v_fmac_f64_e32 v[22:23], v[22:23], v[30:31]
	v_fma_f64 v[32:33], -v[16:17], v[22:23], 1.0
	v_fma_f64 v[30:31], -v[24:25], v[28:29], 1.0
	v_fmac_f64_e32 v[28:29], v[28:29], v[30:31]
	v_div_scale_f64 v[18:19], vcc, v[6:7], v[14:15], v[6:7]
	v_fmac_f64_e32 v[22:23], v[22:23], v[32:33]
	v_fma_f64 v[30:31], -v[24:25], v[28:29], 1.0
	v_div_scale_f64 v[26:27], s[0:1], v[6:7], v[20:21], v[6:7]
	v_mul_f64 v[32:33], v[18:19], v[22:23]
	v_fmac_f64_e32 v[28:29], v[28:29], v[30:31]
	v_fma_f64 v[16:17], -v[16:17], v[32:33], v[18:19]
	v_mul_f64 v[18:19], v[26:27], v[28:29]
	v_div_fmas_f64 v[16:17], v[16:17], v[22:23], v[32:33]
	v_fma_f64 v[22:23], -v[24:25], v[18:19], v[26:27]
	s_mov_b64 vcc, s[0:1]
	v_div_fixup_f64 v[14:15], v[16:17], v[14:15], v[6:7]
	v_div_fmas_f64 v[16:17], v[22:23], v[28:29], v[18:19]
	v_div_fixup_f64 v[16:17], v[16:17], v[20:21], v[6:7]
	s_add_i32 s14, s14, 2
	s_add_i32 s13, s13, 4
	v_mul_f64 v[18:19], v[4:5], v[14:15]
	v_fmac_f64_e32 v[8:9], v[4:5], v[14:15]
	v_mul_f64 v[14:15], v[10:11], v[16:17]
	s_cmp_lg_u32 s14, 30
	v_fmac_f64_e32 v[12:13], v[10:11], v[16:17]
	v_mov_b64_e32 v[4:5], v[18:19]
	v_mov_b64_e32 v[10:11], v[14:15]
	s_cbranch_scc1 .LBB0_17
	v_cvt_f32_f64_e32 v7, v[8:9]
	v_lshl_add_u64 v[4:5], v[2:3], 2, s[6:7]
	v_cvt_f32_f64_e32 v6, v[12:13]
	global_store_dword v[4:5], v7, off
	global_store_dword v[4:5], v6, off offset:2048
	v_add_u32_e32 v4, 0x100, v2
	s_mov_b64 vcc, exec
	s_or_b64 s[8:9], vcc, s[8:9]
	v_mov_b32_e32 v2, v4
	s_andn2_b64 exec, exec, s[8:9]
	s_cbranch_execnz .LBB0_16
	s_or_b64 exec, exec, s[8:9]
